# P9 GEMM K-loop: 8 phases merged pairwise into 4 double phases (half the barriers, 32 MFMAs per MMA segment), A0 refills moved one segment later, vmcnt(8) per load segment
# baseline (speedup 1.0000x reference)
.LBB0_901:
	s_add_u32 s8, s56, 0x8000000
	s_addc_u32 s9, s57, 0
	s_lshl_b32 s10, s10, 5
	s_and_b32 s19, s10, 0x60
	s_mov_b64 s[10:11], 0x80
	s_add_i32 m0, s34, 0x18000
	v_lshl_add_u64 v[8:9], v[8:9], 0, s[10:11]
	s_lshl_b32 s18, s1, 13
	s_lshl_b32 s20, s19, 7
	s_waitcnt vmcnt(2)
	s_barrier
	global_load_lds_dwordx4 v[8:9], off
	v_lshl_add_u64 v[6:7], v[6:7], 0, s[10:11]
	s_add_i32 m0, s34, 0x1a000
	s_add_i32 s48, s34, 0x8000
	s_add_i32 s49, s34, 0xa000
	global_load_lds_dwordx4 v[6:7], off
	v_lshl_add_u64 v[4:5], v[4:5], 0, s[10:11]
	s_mov_b32 m0, s48
	s_add_u32 s16, s42, 0x80080
	global_load_lds_dwordx4 v[4:5], off
	v_lshl_add_u64 v[2:3], v[2:3], 0, s[10:11]
	s_mov_b32 m0, s49
	s_addc_u32 s17, s43, 0
	global_load_lds_dwordx4 v[2:3], off
	s_add_i32 m0, s34, 0x1c000
	v_lshl_add_u64 v[2:3], s[16:17], 0, v[132:133]
	global_load_lds_dwordx4 v[2:3], off
	v_lshl_add_u64 v[2:3], s[16:17], 0, v[136:137]
	s_add_i32 m0, s34, 0x1e000
	s_sext_i32_i8 s65, s0
	global_load_lds_dwordx4 v[2:3], off
	v_and_b32_e32 v2, 15, v10
	v_lshlrev_b32_e32 v3, 1, v14
	v_lshlrev_b32_e32 v4, 2, v10
	v_lshlrev_b32_e32 v5, 6, v10
	s_movk_i32 s0, 0x3c0
	v_lshl_or_b32 v1, s1, 6, v2
	v_lshl_or_b32 v2, v2, 6, v3
	v_and_b32_e32 v4, 32, v4
	v_and_or_b32 v3, v5, s0, v3
	v_bitop3_b32 v147, s20, v3, v4 bitop3:0xf6
	v_lshlrev_b32_e32 v3, 9, v10
	v_bitop3_b32 v2, v2, s18, v4 bitop3:0xde
	v_and_b32_e32 v3, 0x70000, v3
	v_lshlrev_b32_e32 v4, 12, v13
	v_or3_b32 v3, v11, v3, v4
	v_add_u32_e32 v138, v3, v12
	v_lshlrev_b32_e32 v3, 5, v15
	s_waitcnt vmcnt(6)
	v_and_b32_e32 v3, 0xf0000, v3
	v_or3_b32 v3, v11, v3, v4
	s_add_i32 s51, 0, 0x10000
	s_add_i32 s60, 0, 0x14000
	s_ashr_i32 s50, s28, 31
	v_or_b32_e32 v150, s19, v14
	v_mov_b32_e32 v139, v133
	v_add_u32_e32 v140, v3, v12
	v_mov_b32_e32 v141, v133
	v_mov_b64_e32 v[142:143], 0x400
	v_mov_b64_e32 v[144:145], 0x3ff
	v_add_u32_e32 v151, s51, v147
	v_add_u32_e32 v152, 0, v2
	v_add_u32_e32 v153, s60, v147
	s_mov_b32 s61, 0x80000
	s_mov_b64 s[16:17], 0x90000
	s_mov_b32 s62, 0x90000
	s_mov_b64 s[18:19], 0xa0000
	s_mov_b32 s63, 0xa0000
	s_mov_b64 s[20:21], 0xb0000
	s_mov_b32 s64, 0xb0000
	s_barrier

.LBB0_909:
	ds_read_b128 v[154:157], v151
	ds_read_b128 v[158:161], v151 offset:1024
	ds_read_b128 v[162:165], v151 offset:2048
	ds_read_b128 v[166:169], v151 offset:3072
	s_add_u32 s42, s40, 0xfff80080
	s_addc_u32 s43, s41, -1
	s_cmp_eq_u32 s70, 28
	s_cselect_b32 s45, s25, s43
	s_cselect_b32 s44, s66, s42
	s_cselect_b32 s43, s23, s69
	s_cselect_b32 s42, s67, s68
	v_lshl_add_u64 v[148:149], s[40:41], 0, v[138:139]
	s_add_i32 m0, s34, 0xc000
	ds_read_b128 v[170:173], v152
	ds_read_b128 v[174:177], v152 offset:1024
	ds_read_b128 v[178:181], v152 offset:2048
	ds_read_b128 v[182:185], v152 offset:3072
	ds_read_b128 v[186:189], v152 offset:4096
	ds_read_b128 v[190:193], v152 offset:5120
	ds_read_b128 v[194:197], v152 offset:6144
	ds_read_b128 v[198:201], v152 offset:7168
	global_load_lds_dwordx4 v[148:149], off
	v_lshl_add_u64 v[148:149], s[40:41], 0, v[140:141]
	s_add_i32 m0, s34, 0xe000
	s_nop 0
	global_load_lds_dwordx4 v[148:149], off
	ds_read_b128 v[202:205], v153
	ds_read_b128 v[206:209], v153 offset:1024
	ds_read_b128 v[210:213], v153 offset:2048
	ds_read_b128 v[214:217], v153 offset:3072
	s_waitcnt vmcnt(8) lgkmcnt(0)
	s_barrier
	s_setprio 1
	v_mfma_f32_16x16x32_bf16 v[126:129], v[154:157], v[170:173], v[126:129]
	v_mfma_f32_16x16x32_bf16 v[122:125], v[162:165], v[170:173], v[122:125]
	v_mfma_f32_16x16x32_bf16 v[114:117], v[154:157], v[178:181], v[114:117]
	v_mfma_f32_16x16x32_bf16 v[106:109], v[162:165], v[178:181], v[106:109]
	v_mfma_f32_16x16x32_bf16 v[98:101], v[154:157], v[186:189], v[98:101]
	v_mfma_f32_16x16x32_bf16 v[90:93], v[162:165], v[186:189], v[90:93]
	v_mfma_f32_16x16x32_bf16 v[82:85], v[154:157], v[194:197], v[82:85]
	v_mfma_f32_16x16x32_bf16 v[74:77], v[162:165], v[194:197], v[74:77]
	v_mfma_f32_16x16x32_bf16 v[126:129], v[158:161], v[174:177], v[126:129]
	v_mfma_f32_16x16x32_bf16 v[122:125], v[166:169], v[174:177], v[122:125]
	v_mfma_f32_16x16x32_bf16 v[114:117], v[158:161], v[182:185], v[114:117]
	v_mfma_f32_16x16x32_bf16 v[106:109], v[166:169], v[182:185], v[106:109]
	v_mfma_f32_16x16x32_bf16 v[98:101], v[158:161], v[190:193], v[98:101]
	v_mfma_f32_16x16x32_bf16 v[90:93], v[166:169], v[190:193], v[90:93]
	v_mfma_f32_16x16x32_bf16 v[82:85], v[158:161], v[198:201], v[82:85]
	v_mfma_f32_16x16x32_bf16 v[74:77], v[166:169], v[198:201], v[74:77]
	v_mfma_f32_16x16x32_bf16 v[118:121], v[202:205], v[170:173], v[118:121]
	v_mfma_f32_16x16x32_bf16 v[110:113], v[210:213], v[170:173], v[110:113]
	v_mfma_f32_16x16x32_bf16 v[102:105], v[202:205], v[178:181], v[102:105]
	v_mfma_f32_16x16x32_bf16 v[94:97], v[210:213], v[178:181], v[94:97]
	v_mfma_f32_16x16x32_bf16 v[86:89], v[202:205], v[186:189], v[86:89]
	v_mfma_f32_16x16x32_bf16 v[78:81], v[210:213], v[186:189], v[78:81]
	v_mfma_f32_16x16x32_bf16 v[70:73], v[202:205], v[194:197], v[70:73]
	v_mfma_f32_16x16x32_bf16 v[66:69], v[210:213], v[194:197], v[66:69]
	v_mfma_f32_16x16x32_bf16 v[118:121], v[206:209], v[174:177], v[118:121]
	v_mfma_f32_16x16x32_bf16 v[110:113], v[214:217], v[174:177], v[110:113]
	v_mfma_f32_16x16x32_bf16 v[102:105], v[206:209], v[182:185], v[102:105]
	v_mfma_f32_16x16x32_bf16 v[94:97], v[214:217], v[182:185], v[94:97]
	v_mfma_f32_16x16x32_bf16 v[86:89], v[206:209], v[190:193], v[86:89]
	v_mfma_f32_16x16x32_bf16 v[78:81], v[214:217], v[190:193], v[78:81]
	v_mfma_f32_16x16x32_bf16 v[70:73], v[206:209], v[198:201], v[70:73]
	v_mfma_f32_16x16x32_bf16 v[66:69], v[214:217], v[198:201], v[66:69]
	s_setprio 0
	s_barrier
	s_add_i32 s71, s51, s33
	v_lshl_add_u64 v[148:149], s[42:43], 0, v[132:133]
	s_mov_b32 m0, s71
	global_load_lds_dwordx4 v[148:149], off
	v_lshl_add_u64 v[218:219], s[42:43], 0, v[136:137]
	s_add_i32 m0, s71, 0x2000
	s_nop 0
	global_load_lds_dwordx4 v[218:219], off
	s_mov_b32 m0, s34
	v_lshl_add_u64 v[220:221], s[44:45], 0, v[130:131]
	ds_read_b128 v[170:173], v152 offset:16384
	ds_read_b128 v[174:177], v152 offset:17408
	ds_read_b128 v[178:181], v152 offset:18432
	ds_read_b128 v[182:185], v152 offset:19456
	ds_read_b128 v[186:189], v152 offset:20480
	ds_read_b128 v[190:193], v152 offset:21504
	ds_read_b128 v[194:197], v152 offset:22528
	ds_read_b128 v[198:201], v152 offset:23552
	global_load_lds_dwordx4 v[220:221], off
	v_lshl_add_u64 v[222:223], s[44:45], 0, v[134:135]
	s_mov_b32 m0, s35
	s_nop 0
	global_load_lds_dwordx4 v[222:223], off
	s_add_u32 s72, s42, 0x80000
	s_addc_u32 s73, s43, 0
	s_add_i32 s71, s60, s33
	v_lshl_add_u64 v[246:247], s[72:73], 0, v[132:133]
	s_mov_b32 m0, s71
	s_nop 0
	global_load_lds_dwordx4 v[246:247], off
	v_lshl_add_u64 v[246:247], s[72:73], 0, v[136:137]
	s_add_i32 m0, s71, 0x2000
	s_nop 0
	global_load_lds_dwordx4 v[246:247], off
	s_waitcnt vmcnt(8) lgkmcnt(0)
	s_barrier
	s_setprio 1
	v_mfma_f32_16x16x32_bf16 v[62:65], v[154:157], v[170:173], v[62:65]
	v_mfma_f32_16x16x32_bf16 v[58:61], v[162:165], v[170:173], v[58:61]
	v_mfma_f32_16x16x32_bf16 v[54:57], v[154:157], v[178:181], v[54:57]
	v_mfma_f32_16x16x32_bf16 v[46:49], v[162:165], v[178:181], v[46:49]
	v_mfma_f32_16x16x32_bf16 v[38:41], v[154:157], v[186:189], v[38:41]
	v_mfma_f32_16x16x32_bf16 v[30:33], v[162:165], v[186:189], v[30:33]
	v_mfma_f32_16x16x32_bf16 v[22:25], v[154:157], v[194:197], v[22:25]
	v_mfma_f32_16x16x32_bf16 v[14:17], v[162:165], v[194:197], v[14:17]
	v_mfma_f32_16x16x32_bf16 v[62:65], v[158:161], v[174:177], v[62:65]
	v_mfma_f32_16x16x32_bf16 v[58:61], v[166:169], v[174:177], v[58:61]
	v_mfma_f32_16x16x32_bf16 v[54:57], v[158:161], v[182:185], v[54:57]
	v_mfma_f32_16x16x32_bf16 v[46:49], v[166:169], v[182:185], v[46:49]
	v_mfma_f32_16x16x32_bf16 v[38:41], v[158:161], v[190:193], v[38:41]
	v_mfma_f32_16x16x32_bf16 v[30:33], v[166:169], v[190:193], v[30:33]
	v_mfma_f32_16x16x32_bf16 v[22:25], v[158:161], v[198:201], v[22:25]
	v_mfma_f32_16x16x32_bf16 v[14:17], v[166:169], v[198:201], v[14:17]
	v_mfma_f32_16x16x32_bf16 v[50:53], v[202:205], v[170:173], v[50:53]
	v_mfma_f32_16x16x32_bf16 v[42:45], v[210:213], v[170:173], v[42:45]
	v_mfma_f32_16x16x32_bf16 v[34:37], v[202:205], v[178:181], v[34:37]
	v_mfma_f32_16x16x32_bf16 v[26:29], v[210:213], v[178:181], v[26:29]
	v_mfma_f32_16x16x32_bf16 v[18:21], v[202:205], v[186:189], v[18:21]
	v_mfma_f32_16x16x32_bf16 v[10:13], v[210:213], v[186:189], v[10:13]
	v_mfma_f32_16x16x32_bf16 v[6:9], v[202:205], v[194:197], v[6:9]
	v_mfma_f32_16x16x32_bf16 v[2:5], v[210:213], v[194:197], v[2:5]
	v_mfma_f32_16x16x32_bf16 v[50:53], v[206:209], v[174:177], v[50:53]
	v_mfma_f32_16x16x32_bf16 v[42:45], v[214:217], v[174:177], v[42:45]
	v_mfma_f32_16x16x32_bf16 v[34:37], v[206:209], v[182:185], v[34:37]
	v_mfma_f32_16x16x32_bf16 v[26:29], v[214:217], v[182:185], v[26:29]
	v_mfma_f32_16x16x32_bf16 v[18:21], v[206:209], v[190:193], v[18:21]
	v_mfma_f32_16x16x32_bf16 v[10:13], v[214:217], v[190:193], v[10:13]
	v_mfma_f32_16x16x32_bf16 v[6:9], v[206:209], v[198:201], v[6:9]
	v_mfma_f32_16x16x32_bf16 v[2:5], v[214:217], v[198:201], v[2:5]
	s_setprio 0
	s_add_i32 s71, 0, 0x18000
	v_add_u32_e32 v166, s71, v147
	s_barrier
	ds_read_b128 v[154:157], v166
	ds_read_b128 v[158:161], v166 offset:1024
	ds_read_b128 v[162:165], v166 offset:2048
	ds_read_b128 v[166:169], v166 offset:3072
	s_add_u32 s44, s44, 0x80000
	s_addc_u32 s45, s45, 0
	s_mov_b32 m0, s39
	v_lshl_add_u64 v[246:247], s[44:45], 0, v[130:131]
	ds_read_b128 v[170:173], v152 offset:32768
	ds_read_b128 v[174:177], v152 offset:33792
	ds_read_b128 v[178:181], v152 offset:34816
	ds_read_b128 v[182:185], v152 offset:35840
	ds_read_b128 v[186:189], v152 offset:36864
	ds_read_b128 v[190:193], v152 offset:37888
	ds_read_b128 v[194:197], v152 offset:38912
	ds_read_b128 v[198:201], v152 offset:39936
	global_load_lds_dwordx4 v[246:247], off
	v_lshl_add_u64 v[246:247], s[44:45], 0, v[134:135]
	s_mov_b32 m0, s46
	s_nop 0
	global_load_lds_dwordx4 v[246:247], off
	s_add_i32 s44, 0, 0x1c000
	v_add_u32_e32 v214, s44, v147
	ds_read_b128 v[202:205], v214
	ds_read_b128 v[206:209], v214 offset:1024
	ds_read_b128 v[210:213], v214 offset:2048
	ds_read_b128 v[214:217], v214 offset:3072
	s_waitcnt vmcnt(8) lgkmcnt(0)
	s_barrier
	s_setprio 1
	v_mfma_f32_16x16x32_bf16 v[126:129], v[154:157], v[170:173], v[126:129]
	v_mfma_f32_16x16x32_bf16 v[122:125], v[162:165], v[170:173], v[122:125]
	v_mfma_f32_16x16x32_bf16 v[114:117], v[154:157], v[178:181], v[114:117]
	v_mfma_f32_16x16x32_bf16 v[106:109], v[162:165], v[178:181], v[106:109]
	v_mfma_f32_16x16x32_bf16 v[98:101], v[154:157], v[186:189], v[98:101]
	v_mfma_f32_16x16x32_bf16 v[90:93], v[162:165], v[186:189], v[90:93]
	v_mfma_f32_16x16x32_bf16 v[82:85], v[154:157], v[194:197], v[82:85]
	v_mfma_f32_16x16x32_bf16 v[74:77], v[162:165], v[194:197], v[74:77]
	v_mfma_f32_16x16x32_bf16 v[126:129], v[158:161], v[174:177], v[126:129]
	v_mfma_f32_16x16x32_bf16 v[122:125], v[166:169], v[174:177], v[122:125]
	v_mfma_f32_16x16x32_bf16 v[114:117], v[158:161], v[182:185], v[114:117]
	v_mfma_f32_16x16x32_bf16 v[106:109], v[166:169], v[182:185], v[106:109]
	v_mfma_f32_16x16x32_bf16 v[98:101], v[158:161], v[190:193], v[98:101]
	v_mfma_f32_16x16x32_bf16 v[90:93], v[166:169], v[190:193], v[90:93]
	v_mfma_f32_16x16x32_bf16 v[82:85], v[158:161], v[198:201], v[82:85]
	v_mfma_f32_16x16x32_bf16 v[74:77], v[166:169], v[198:201], v[74:77]
	v_mfma_f32_16x16x32_bf16 v[118:121], v[202:205], v[170:173], v[118:121]
	v_mfma_f32_16x16x32_bf16 v[110:113], v[210:213], v[170:173], v[110:113]
	v_mfma_f32_16x16x32_bf16 v[102:105], v[202:205], v[178:181], v[102:105]
	v_mfma_f32_16x16x32_bf16 v[94:97], v[210:213], v[178:181], v[94:97]
	v_mfma_f32_16x16x32_bf16 v[86:89], v[202:205], v[186:189], v[86:89]
	v_mfma_f32_16x16x32_bf16 v[78:81], v[210:213], v[186:189], v[78:81]
	v_mfma_f32_16x16x32_bf16 v[70:73], v[202:205], v[194:197], v[70:73]
	v_mfma_f32_16x16x32_bf16 v[66:69], v[210:213], v[194:197], v[66:69]
	v_mfma_f32_16x16x32_bf16 v[118:121], v[206:209], v[174:177], v[118:121]
	v_mfma_f32_16x16x32_bf16 v[110:113], v[214:217], v[174:177], v[110:113]
	v_mfma_f32_16x16x32_bf16 v[102:105], v[206:209], v[182:185], v[102:105]
	v_mfma_f32_16x16x32_bf16 v[94:97], v[214:217], v[182:185], v[94:97]
	v_mfma_f32_16x16x32_bf16 v[86:89], v[206:209], v[190:193], v[86:89]
	v_mfma_f32_16x16x32_bf16 v[78:81], v[214:217], v[190:193], v[78:81]
	v_mfma_f32_16x16x32_bf16 v[70:73], v[206:209], v[198:201], v[70:73]
	v_mfma_f32_16x16x32_bf16 v[66:69], v[214:217], v[198:201], v[66:69]
	s_setprio 0
	s_barrier
	s_add_i32 s45, s71, s33
	v_lshl_add_u64 v[148:149], v[148:149], 0, s[10:11]
	s_mov_b32 m0, s45
	global_load_lds_dwordx4 v[148:149], off
	v_lshl_add_u64 v[148:149], v[218:219], 0, s[10:11]
	s_add_i32 m0, s45, 0x2000
	s_nop 0
	global_load_lds_dwordx4 v[148:149], off
	s_mov_b32 m0, s48
	v_lshl_add_u64 v[148:149], v[220:221], 0, s[10:11]
	ds_read_b128 v[170:173], v152 offset:49152
	ds_read_b128 v[174:177], v152 offset:50176
	ds_read_b128 v[178:181], v152 offset:51200
	ds_read_b128 v[182:185], v152 offset:52224
	ds_read_b128 v[186:189], v152 offset:53248
	ds_read_b128 v[190:193], v152 offset:54272
	ds_read_b128 v[194:197], v152 offset:55296
	ds_read_b128 v[198:201], v152 offset:56320
	global_load_lds_dwordx4 v[148:149], off
	v_lshl_add_u64 v[148:149], v[222:223], 0, s[10:11]
	s_mov_b32 m0, s49
	s_nop 0
	global_load_lds_dwordx4 v[148:149], off
	s_add_u32 s42, s42, 0x80080
	s_addc_u32 s43, s43, 0
	s_add_i32 s44, s44, s33
	v_lshl_add_u64 v[148:149], s[42:43], 0, v[132:133]
	s_mov_b32 m0, s44
	s_nop 0
	global_load_lds_dwordx4 v[148:149], off
	v_lshl_add_u64 v[148:149], s[42:43], 0, v[136:137]
	s_add_i32 m0, s44, 0x2000
	s_nop 0
	global_load_lds_dwordx4 v[148:149], off
	s_waitcnt vmcnt(8) lgkmcnt(0)
	s_barrier
	s_setprio 1
	v_mfma_f32_16x16x32_bf16 v[62:65], v[154:157], v[170:173], v[62:65]
	v_mfma_f32_16x16x32_bf16 v[58:61], v[162:165], v[170:173], v[58:61]
	v_mfma_f32_16x16x32_bf16 v[54:57], v[154:157], v[178:181], v[54:57]
	v_mfma_f32_16x16x32_bf16 v[46:49], v[162:165], v[178:181], v[46:49]
	v_mfma_f32_16x16x32_bf16 v[38:41], v[154:157], v[186:189], v[38:41]
	v_mfma_f32_16x16x32_bf16 v[30:33], v[162:165], v[186:189], v[30:33]
	v_mfma_f32_16x16x32_bf16 v[22:25], v[154:157], v[194:197], v[22:25]
	v_mfma_f32_16x16x32_bf16 v[14:17], v[162:165], v[194:197], v[14:17]
	v_mfma_f32_16x16x32_bf16 v[62:65], v[158:161], v[174:177], v[62:65]
	v_mfma_f32_16x16x32_bf16 v[58:61], v[166:169], v[174:177], v[58:61]
	v_mfma_f32_16x16x32_bf16 v[54:57], v[158:161], v[182:185], v[54:57]
	v_mfma_f32_16x16x32_bf16 v[46:49], v[166:169], v[182:185], v[46:49]
	v_mfma_f32_16x16x32_bf16 v[38:41], v[158:161], v[190:193], v[38:41]
	v_mfma_f32_16x16x32_bf16 v[30:33], v[166:169], v[190:193], v[30:33]
	v_mfma_f32_16x16x32_bf16 v[22:25], v[158:161], v[198:201], v[22:25]
	v_mfma_f32_16x16x32_bf16 v[14:17], v[166:169], v[198:201], v[14:17]
	v_mfma_f32_16x16x32_bf16 v[50:53], v[202:205], v[170:173], v[50:53]
	v_mfma_f32_16x16x32_bf16 v[42:45], v[210:213], v[170:173], v[42:45]
	v_mfma_f32_16x16x32_bf16 v[34:37], v[202:205], v[178:181], v[34:37]
	v_mfma_f32_16x16x32_bf16 v[26:29], v[210:213], v[178:181], v[26:29]
	v_mfma_f32_16x16x32_bf16 v[18:21], v[202:205], v[186:189], v[18:21]
	v_mfma_f32_16x16x32_bf16 v[10:13], v[210:213], v[186:189], v[10:13]
	v_mfma_f32_16x16x32_bf16 v[6:9], v[202:205], v[194:197], v[6:9]
	v_mfma_f32_16x16x32_bf16 v[2:5], v[210:213], v[194:197], v[2:5]
	v_mfma_f32_16x16x32_bf16 v[50:53], v[206:209], v[174:177], v[50:53]
	v_mfma_f32_16x16x32_bf16 v[42:45], v[214:217], v[174:177], v[42:45]
	v_mfma_f32_16x16x32_bf16 v[34:37], v[206:209], v[182:185], v[34:37]
	v_mfma_f32_16x16x32_bf16 v[26:29], v[214:217], v[182:185], v[26:29]
	v_mfma_f32_16x16x32_bf16 v[18:21], v[206:209], v[190:193], v[18:21]
	v_mfma_f32_16x16x32_bf16 v[10:13], v[214:217], v[190:193], v[10:13]
	v_mfma_f32_16x16x32_bf16 v[6:9], v[206:209], v[198:201], v[6:9]
	v_mfma_f32_16x16x32_bf16 v[2:5], v[214:217], v[198:201], v[2:5]
	s_setprio 0
	s_add_i32 s70, s70, 2
	s_add_u32 s40, s40, 0x100
	s_addc_u32 s41, s41, 0
	s_add_u32 s68, s68, 0x100
	s_addc_u32 s69, s69, 0
	s_cmp_gt_u32 s70, 29
	s_barrier
	s_cbranch_scc0 .LBB0_909
	v_lshl_add_u32 v154, s38, 8, v1
	v_lshl_or_b32 v148, s65, 8, v150
	v_ashrrev_i32_e32 v155, 31, v154
	v_ashrrev_i32_e32 v149, 31, v148
	v_lshlrev_b64 v[156:157], 12, v[154:155]
	v_lshl_add_u64 v[156:157], s[8:9], 0, v[156:157]
	v_lshlrev_b64 v[158:159], 1, v[148:149]
	v_lshl_add_u64 v[148:149], v[156:157], 0, v[158:159]
	v_cvt_pk_bf16_f32 v126, v126, v127
	v_cvt_pk_bf16_f32 v127, v128, v129
	v_cvt_pk_bf16_f32 v128, v122, v123
	v_cvt_pk_bf16_f32 v129, v124, v125
	global_store_dwordx4 v[148:149], v[126:129], off
	v_cvt_pk_bf16_f32 v118, v118, v119
	v_cvt_pk_bf16_f32 v119, v120, v121
	v_cvt_pk_bf16_f32 v120, v110, v111
	v_or_b32_e32 v110, 16, v154
	v_ashrrev_i32_e32 v111, 31, v110
	v_lshlrev_b64 v[110:111], 12, v[110:111]
	v_lshl_add_u64 v[110:111], s[8:9], 0, v[110:111]
	v_cvt_pk_bf16_f32 v121, v112, v113
	global_store_dwordx4 v[148:149], v[118:121], off offset:256
	s_mov_b32 s65, s22
	s_mov_b32 s38, s24
	v_lshl_add_u64 v[118:119], v[110:111], 0, v[158:159]
	v_cvt_pk_bf16_f32 v110, v114, v115
	v_cvt_pk_bf16_f32 v111, v116, v117
	v_cvt_pk_bf16_f32 v112, v106, v107
	v_cvt_pk_bf16_f32 v113, v108, v109
	global_store_dwordx4 v[118:119], v[110:113], off
	v_cvt_pk_bf16_f32 v102, v102, v103
	v_cvt_pk_bf16_f32 v103, v104, v105
	v_cvt_pk_bf16_f32 v104, v94, v95
	v_or_b32_e32 v94, 32, v154
	v_ashrrev_i32_e32 v95, 31, v94
	v_lshlrev_b64 v[94:95], 12, v[94:95]
	v_lshl_add_u64 v[94:95], s[8:9], 0, v[94:95]
	v_cvt_pk_bf16_f32 v105, v96, v97
	global_store_dwordx4 v[118:119], v[102:105], off offset:256
	s_mov_b64 s[42:43], s[36:37]
	s_mov_b64 s[40:41], s[26:27]
	v_lshl_add_u64 v[102:103], v[94:95], 0, v[158:159]
	v_cvt_pk_bf16_f32 v94, v98, v99
	v_cvt_pk_bf16_f32 v95, v100, v101
	v_cvt_pk_bf16_f32 v96, v90, v91
	v_cvt_pk_bf16_f32 v97, v92, v93
	global_store_dwordx4 v[102:103], v[94:97], off
	v_cvt_pk_bf16_f32 v86, v86, v87
	v_cvt_pk_bf16_f32 v87, v88, v89
	v_cvt_pk_bf16_f32 v88, v78, v79
	v_or_b32_e32 v78, 48, v154
	v_ashrrev_i32_e32 v79, 31, v78
	v_lshlrev_b64 v[78:79], 12, v[78:79]
	v_lshl_add_u64 v[78:79], s[8:9], 0, v[78:79]
	v_cvt_pk_bf16_f32 v89, v80, v81
	global_store_dwordx4 v[102:103], v[86:89], off offset:256
	s_nop 1
	v_lshl_add_u64 v[86:87], v[78:79], 0, v[158:159]
	v_cvt_pk_bf16_f32 v78, v82, v83
	v_cvt_pk_bf16_f32 v79, v84, v85
	v_cvt_pk_bf16_f32 v80, v74, v75
	v_cvt_pk_bf16_f32 v81, v76, v77
	global_store_dwordx4 v[86:87], v[78:81], off
	v_cvt_pk_bf16_f32 v70, v70, v71
	v_cvt_pk_bf16_f32 v71, v72, v73
	v_cvt_pk_bf16_f32 v72, v66, v67
	v_cvt_pk_bf16_f32 v73, v68, v69
	global_store_dwordx4 v[86:87], v[70:73], off offset:256
	v_cvt_pk_bf16_f32 v62, v62, v63
	v_cvt_pk_bf16_f32 v63, v64, v65
	v_cvt_pk_bf16_f32 v64, v58, v59
	v_add_co_u32_e32 v58, vcc, s61, v148
	v_lshl_add_u64 v[66:67], v[148:149], 0, s[6:7]
	s_nop 0
	v_addc_co_u32_e32 v59, vcc, 0, v149, vcc
	v_cvt_pk_bf16_f32 v65, v60, v61
	global_store_dwordx4 v[58:59], v[62:65], off
	v_cvt_pk_bf16_f32 v50, v50, v51
	v_cvt_pk_bf16_f32 v51, v52, v53
	v_cvt_pk_bf16_f32 v52, v42, v43
	v_cvt_pk_bf16_f32 v53, v44, v45
	global_store_dwordx4 v[66:67], v[50:53], off offset:256
	v_cvt_pk_bf16_f32 v42, v54, v55
	v_cvt_pk_bf16_f32 v43, v56, v57
	v_cvt_pk_bf16_f32 v44, v46, v47
	v_add_co_u32_e32 v46, vcc, s62, v148
	s_nop 0
	v_lshl_add_u64 v[50:51], v[148:149], 0, s[16:17]
	v_addc_co_u32_e32 v47, vcc, 0, v149, vcc
	v_cvt_pk_bf16_f32 v45, v48, v49
	global_store_dwordx4 v[46:47], v[42:45], off
	v_cvt_pk_bf16_f32 v34, v34, v35
	v_cvt_pk_bf16_f32 v35, v36, v37
	v_cvt_pk_bf16_f32 v36, v26, v27
	v_cvt_pk_bf16_f32 v37, v28, v29
	global_store_dwordx4 v[50:51], v[34:37], off offset:256
	v_cvt_pk_bf16_f32 v26, v38, v39
	v_cvt_pk_bf16_f32 v27, v40, v41
	v_cvt_pk_bf16_f32 v28, v30, v31
	v_add_co_u32_e32 v30, vcc, s63, v148
	s_nop 0
	v_lshl_add_u64 v[34:35], v[148:149], 0, s[18:19]
	v_addc_co_u32_e32 v31, vcc, 0, v149, vcc
	v_cvt_pk_bf16_f32 v29, v32, v33
	global_store_dwordx4 v[30:31], v[26:29], off
	v_cvt_pk_bf16_f32 v18, v18, v19
	v_cvt_pk_bf16_f32 v19, v20, v21
	v_cvt_pk_bf16_f32 v20, v10, v11
	v_cvt_pk_bf16_f32 v21, v12, v13
	global_store_dwordx4 v[34:35], v[18:21], off offset:256
	v_cvt_pk_bf16_f32 v10, v22, v23
	v_cvt_pk_bf16_f32 v11, v24, v25
	v_cvt_pk_bf16_f32 v12, v14, v15
	v_add_co_u32_e32 v14, vcc, s64, v148
	s_nop 0
	v_lshl_add_u64 v[18:19], v[148:149], 0, s[20:21]
	v_addc_co_u32_e32 v15, vcc, 0, v149, vcc
	s_and_b64 vcc, exec, s[0:1]
	v_cvt_pk_bf16_f32 v13, v16, v17
	global_store_dwordx4 v[14:15], v[10:13], off
	v_cvt_pk_bf16_f32 v6, v6, v7
	v_cvt_pk_bf16_f32 v7, v8, v9
	v_cvt_pk_bf16_f32 v8, v2, v3
	v_cvt_pk_bf16_f32 v9, v4, v5
	global_store_dwordx4 v[18:19], v[6:9], off offset:256
	s_cbranch_vccz .LBB0_902
	s_waitcnt vmcnt(0)
	s_cmpk_gt_u32 s3, 0xff
	s_cbranch_scc1 .LBB0_913
	s_barrier
